# waves 4-7 keep s_setprio 2 (was 1) after the solve
# speedup vs baseline: 1.0027x; 1.0027x over previous
.Lsx0_d:
	s_setprio 3
	v_lshrrev_b32_e32 v96, 6, v198
	v_mul_u32_u24_e32 v96, 0x500, v96
	v_mad_u32_u24 v96, v145, 20, v96
	v_and_b32_e32 v97, 15, v198
	v_lshl_add_u32 v96, v97, 1, v96
	v_add_u32_e32 v96, 0x10a00, v96
	s_waitcnt lgkmcnt(0)
	s_nop 1
	v_fmac_f32_dpp v30, v30, v80 row_newbcast:0 row_mask:0xf bank_mask:0xf
	v_fmac_f32_dpp v31, v31, v80 row_newbcast:0 row_mask:0xf bank_mask:0xf
	v_fmac_f32_dpp v32, v32, v80 row_newbcast:0 row_mask:0xf bank_mask:0xf
	v_fmac_f32_dpp v33, v33, v80 row_newbcast:0 row_mask:0xf bank_mask:0xf
	v_fmac_f32_dpp v30, v30, v81 row_newbcast:1 row_mask:0xf bank_mask:0xf
	v_fmac_f32_dpp v31, v31, v81 row_newbcast:1 row_mask:0xf bank_mask:0xf
	v_fmac_f32_dpp v32, v32, v81 row_newbcast:1 row_mask:0xf bank_mask:0xf
	v_fmac_f32_dpp v33, v33, v81 row_newbcast:1 row_mask:0xf bank_mask:0xf
	v_fmac_f32_dpp v30, v30, v82 row_newbcast:2 row_mask:0xf bank_mask:0xf
	v_fmac_f32_dpp v31, v31, v82 row_newbcast:2 row_mask:0xf bank_mask:0xf
	v_fmac_f32_dpp v32, v32, v82 row_newbcast:2 row_mask:0xf bank_mask:0xf
	v_fmac_f32_dpp v33, v33, v82 row_newbcast:2 row_mask:0xf bank_mask:0xf
	v_fmac_f32_dpp v30, v30, v83 row_newbcast:3 row_mask:0xf bank_mask:0xf
	v_fmac_f32_dpp v31, v31, v83 row_newbcast:3 row_mask:0xf bank_mask:0xf
	v_fmac_f32_dpp v32, v32, v83 row_newbcast:3 row_mask:0xf bank_mask:0xf
	v_fmac_f32_dpp v33, v33, v83 row_newbcast:3 row_mask:0xf bank_mask:0xf
	v_fmac_f32_dpp v30, v30, v84 row_newbcast:4 row_mask:0xf bank_mask:0xf
	v_fmac_f32_dpp v31, v31, v84 row_newbcast:4 row_mask:0xf bank_mask:0xf
	v_fmac_f32_dpp v32, v32, v84 row_newbcast:4 row_mask:0xf bank_mask:0xf
	v_fmac_f32_dpp v33, v33, v84 row_newbcast:4 row_mask:0xf bank_mask:0xf
	v_fmac_f32_dpp v30, v30, v85 row_newbcast:5 row_mask:0xf bank_mask:0xf
	v_fmac_f32_dpp v31, v31, v85 row_newbcast:5 row_mask:0xf bank_mask:0xf
	v_fmac_f32_dpp v32, v32, v85 row_newbcast:5 row_mask:0xf bank_mask:0xf
	v_fmac_f32_dpp v33, v33, v85 row_newbcast:5 row_mask:0xf bank_mask:0xf
	v_fmac_f32_dpp v30, v30, v86 row_newbcast:6 row_mask:0xf bank_mask:0xf
	v_fmac_f32_dpp v31, v31, v86 row_newbcast:6 row_mask:0xf bank_mask:0xf
	v_fmac_f32_dpp v32, v32, v86 row_newbcast:6 row_mask:0xf bank_mask:0xf
	v_fmac_f32_dpp v33, v33, v86 row_newbcast:6 row_mask:0xf bank_mask:0xf
	v_fmac_f32_dpp v30, v30, v87 row_newbcast:7 row_mask:0xf bank_mask:0xf
	v_fmac_f32_dpp v31, v31, v87 row_newbcast:7 row_mask:0xf bank_mask:0xf
	v_fmac_f32_dpp v32, v32, v87 row_newbcast:7 row_mask:0xf bank_mask:0xf
	v_fmac_f32_dpp v33, v33, v87 row_newbcast:7 row_mask:0xf bank_mask:0xf
	v_fmac_f32_dpp v30, v30, v88 row_newbcast:8 row_mask:0xf bank_mask:0xf
	v_fmac_f32_dpp v31, v31, v88 row_newbcast:8 row_mask:0xf bank_mask:0xf
	v_fmac_f32_dpp v32, v32, v88 row_newbcast:8 row_mask:0xf bank_mask:0xf
	v_fmac_f32_dpp v33, v33, v88 row_newbcast:8 row_mask:0xf bank_mask:0xf
	v_fmac_f32_dpp v30, v30, v89 row_newbcast:9 row_mask:0xf bank_mask:0xf
	v_fmac_f32_dpp v31, v31, v89 row_newbcast:9 row_mask:0xf bank_mask:0xf
	v_fmac_f32_dpp v32, v32, v89 row_newbcast:9 row_mask:0xf bank_mask:0xf
	v_fmac_f32_dpp v33, v33, v89 row_newbcast:9 row_mask:0xf bank_mask:0xf
	v_fmac_f32_dpp v30, v30, v90 row_newbcast:10 row_mask:0xf bank_mask:0xf
	v_fmac_f32_dpp v31, v31, v90 row_newbcast:10 row_mask:0xf bank_mask:0xf
	v_fmac_f32_dpp v32, v32, v90 row_newbcast:10 row_mask:0xf bank_mask:0xf
	v_fmac_f32_dpp v33, v33, v90 row_newbcast:10 row_mask:0xf bank_mask:0xf
	v_fmac_f32_dpp v30, v30, v91 row_newbcast:11 row_mask:0xf bank_mask:0xf
	v_fmac_f32_dpp v31, v31, v91 row_newbcast:11 row_mask:0xf bank_mask:0xf
	v_fmac_f32_dpp v32, v32, v91 row_newbcast:11 row_mask:0xf bank_mask:0xf
	v_fmac_f32_dpp v33, v33, v91 row_newbcast:11 row_mask:0xf bank_mask:0xf
	v_fmac_f32_dpp v30, v30, v92 row_newbcast:12 row_mask:0xf bank_mask:0xf
	v_fmac_f32_dpp v31, v31, v92 row_newbcast:12 row_mask:0xf bank_mask:0xf
	v_fmac_f32_dpp v32, v32, v92 row_newbcast:12 row_mask:0xf bank_mask:0xf
	v_fmac_f32_dpp v33, v33, v92 row_newbcast:12 row_mask:0xf bank_mask:0xf
	v_fmac_f32_dpp v30, v30, v93 row_newbcast:13 row_mask:0xf bank_mask:0xf
	v_fmac_f32_dpp v31, v31, v93 row_newbcast:13 row_mask:0xf bank_mask:0xf
	v_fmac_f32_dpp v32, v32, v93 row_newbcast:13 row_mask:0xf bank_mask:0xf
	v_fmac_f32_dpp v33, v33, v93 row_newbcast:13 row_mask:0xf bank_mask:0xf
	v_fmac_f32_dpp v30, v30, v94 row_newbcast:14 row_mask:0xf bank_mask:0xf
	v_fmac_f32_dpp v31, v31, v94 row_newbcast:14 row_mask:0xf bank_mask:0xf
	v_fmac_f32_dpp v32, v32, v94 row_newbcast:14 row_mask:0xf bank_mask:0xf
	v_fmac_f32_dpp v33, v33, v94 row_newbcast:14 row_mask:0xf bank_mask:0xf
	v_cvt_pk_bf16_f32 v80, v30, v31
	v_cvt_pk_bf16_f32 v81, v32, v33
	ds_write_b16 v96, v80 offset:0
	ds_write_b16_d16_hi v96, v80 offset:80
	ds_write_b16 v96, v81 offset:160
	ds_write_b16_d16_hi v96, v81 offset:240
	s_setprio 2

.Lis1b:
	v_cvt_pk_bf16_f32 v240, v236, v237
	global_store_dword v[238:239], v240, off
	v_cvt_pk_bf16_f32 v245, v234, v235
	global_store_dword v[238:239], v245, off offset:-1024
	s_setprio 3
	v_lshrrev_b32_e32 v96, 6, v198
	v_mul_u32_u24_e32 v96, 0x500, v96
	v_mad_u32_u24 v96, v145, 20, v96
	v_and_b32_e32 v97, 15, v198
	v_lshl_add_u32 v96, v97, 1, v96
	v_add_u32_e32 v96, 0x10a00, v96
	s_waitcnt lgkmcnt(0)
	s_nop 1
	v_fmac_f32_dpp v30, v30, v80 row_newbcast:0 row_mask:0xf bank_mask:0xf
	v_fmac_f32_dpp v31, v31, v80 row_newbcast:0 row_mask:0xf bank_mask:0xf
	v_fmac_f32_dpp v32, v32, v80 row_newbcast:0 row_mask:0xf bank_mask:0xf
	v_fmac_f32_dpp v33, v33, v80 row_newbcast:0 row_mask:0xf bank_mask:0xf
	v_fmac_f32_dpp v30, v30, v81 row_newbcast:1 row_mask:0xf bank_mask:0xf
	v_fmac_f32_dpp v31, v31, v81 row_newbcast:1 row_mask:0xf bank_mask:0xf
	v_fmac_f32_dpp v32, v32, v81 row_newbcast:1 row_mask:0xf bank_mask:0xf
	v_fmac_f32_dpp v33, v33, v81 row_newbcast:1 row_mask:0xf bank_mask:0xf
	v_fmac_f32_dpp v30, v30, v82 row_newbcast:2 row_mask:0xf bank_mask:0xf
	v_fmac_f32_dpp v31, v31, v82 row_newbcast:2 row_mask:0xf bank_mask:0xf
	v_fmac_f32_dpp v32, v32, v82 row_newbcast:2 row_mask:0xf bank_mask:0xf
	v_fmac_f32_dpp v33, v33, v82 row_newbcast:2 row_mask:0xf bank_mask:0xf
	v_fmac_f32_dpp v30, v30, v83 row_newbcast:3 row_mask:0xf bank_mask:0xf
	v_fmac_f32_dpp v31, v31, v83 row_newbcast:3 row_mask:0xf bank_mask:0xf
	v_fmac_f32_dpp v32, v32, v83 row_newbcast:3 row_mask:0xf bank_mask:0xf
	v_fmac_f32_dpp v33, v33, v83 row_newbcast:3 row_mask:0xf bank_mask:0xf
	v_fmac_f32_dpp v30, v30, v84 row_newbcast:4 row_mask:0xf bank_mask:0xf
	v_fmac_f32_dpp v31, v31, v84 row_newbcast:4 row_mask:0xf bank_mask:0xf
	v_fmac_f32_dpp v32, v32, v84 row_newbcast:4 row_mask:0xf bank_mask:0xf
	v_fmac_f32_dpp v33, v33, v84 row_newbcast:4 row_mask:0xf bank_mask:0xf
	v_fmac_f32_dpp v30, v30, v85 row_newbcast:5 row_mask:0xf bank_mask:0xf
	v_fmac_f32_dpp v31, v31, v85 row_newbcast:5 row_mask:0xf bank_mask:0xf
	v_fmac_f32_dpp v32, v32, v85 row_newbcast:5 row_mask:0xf bank_mask:0xf
	v_fmac_f32_dpp v33, v33, v85 row_newbcast:5 row_mask:0xf bank_mask:0xf
	v_fmac_f32_dpp v30, v30, v86 row_newbcast:6 row_mask:0xf bank_mask:0xf
	v_fmac_f32_dpp v31, v31, v86 row_newbcast:6 row_mask:0xf bank_mask:0xf
	v_fmac_f32_dpp v32, v32, v86 row_newbcast:6 row_mask:0xf bank_mask:0xf
	v_fmac_f32_dpp v33, v33, v86 row_newbcast:6 row_mask:0xf bank_mask:0xf
	v_fmac_f32_dpp v30, v30, v87 row_newbcast:7 row_mask:0xf bank_mask:0xf
	v_fmac_f32_dpp v31, v31, v87 row_newbcast:7 row_mask:0xf bank_mask:0xf
	v_fmac_f32_dpp v32, v32, v87 row_newbcast:7 row_mask:0xf bank_mask:0xf
	v_fmac_f32_dpp v33, v33, v87 row_newbcast:7 row_mask:0xf bank_mask:0xf
	v_fmac_f32_dpp v30, v30, v88 row_newbcast:8 row_mask:0xf bank_mask:0xf
	v_fmac_f32_dpp v31, v31, v88 row_newbcast:8 row_mask:0xf bank_mask:0xf
	v_fmac_f32_dpp v32, v32, v88 row_newbcast:8 row_mask:0xf bank_mask:0xf
	v_fmac_f32_dpp v33, v33, v88 row_newbcast:8 row_mask:0xf bank_mask:0xf
	v_fmac_f32_dpp v30, v30, v89 row_newbcast:9 row_mask:0xf bank_mask:0xf
	v_fmac_f32_dpp v31, v31, v89 row_newbcast:9 row_mask:0xf bank_mask:0xf
	v_fmac_f32_dpp v32, v32, v89 row_newbcast:9 row_mask:0xf bank_mask:0xf
	v_fmac_f32_dpp v33, v33, v89 row_newbcast:9 row_mask:0xf bank_mask:0xf
	v_fmac_f32_dpp v30, v30, v90 row_newbcast:10 row_mask:0xf bank_mask:0xf
	v_fmac_f32_dpp v31, v31, v90 row_newbcast:10 row_mask:0xf bank_mask:0xf
	v_fmac_f32_dpp v32, v32, v90 row_newbcast:10 row_mask:0xf bank_mask:0xf
	v_fmac_f32_dpp v33, v33, v90 row_newbcast:10 row_mask:0xf bank_mask:0xf
	v_fmac_f32_dpp v30, v30, v91 row_newbcast:11 row_mask:0xf bank_mask:0xf
	v_fmac_f32_dpp v31, v31, v91 row_newbcast:11 row_mask:0xf bank_mask:0xf
	v_fmac_f32_dpp v32, v32, v91 row_newbcast:11 row_mask:0xf bank_mask:0xf
	v_fmac_f32_dpp v33, v33, v91 row_newbcast:11 row_mask:0xf bank_mask:0xf
	v_fmac_f32_dpp v30, v30, v92 row_newbcast:12 row_mask:0xf bank_mask:0xf
	v_fmac_f32_dpp v31, v31, v92 row_newbcast:12 row_mask:0xf bank_mask:0xf
	v_fmac_f32_dpp v32, v32, v92 row_newbcast:12 row_mask:0xf bank_mask:0xf
	v_fmac_f32_dpp v33, v33, v92 row_newbcast:12 row_mask:0xf bank_mask:0xf
	v_fmac_f32_dpp v30, v30, v93 row_newbcast:13 row_mask:0xf bank_mask:0xf
	v_fmac_f32_dpp v31, v31, v93 row_newbcast:13 row_mask:0xf bank_mask:0xf
	v_fmac_f32_dpp v32, v32, v93 row_newbcast:13 row_mask:0xf bank_mask:0xf
	v_fmac_f32_dpp v33, v33, v93 row_newbcast:13 row_mask:0xf bank_mask:0xf
	v_fmac_f32_dpp v30, v30, v94 row_newbcast:14 row_mask:0xf bank_mask:0xf
	v_fmac_f32_dpp v31, v31, v94 row_newbcast:14 row_mask:0xf bank_mask:0xf
	v_fmac_f32_dpp v32, v32, v94 row_newbcast:14 row_mask:0xf bank_mask:0xf
	v_fmac_f32_dpp v33, v33, v94 row_newbcast:14 row_mask:0xf bank_mask:0xf
	v_cvt_pk_bf16_f32 v80, v30, v31
	v_cvt_pk_bf16_f32 v81, v32, v33
	ds_write_b16 v96, v80 offset:5120
	ds_write_b16_d16_hi v96, v80 offset:5200
	ds_write_b16 v96, v81 offset:5280
	ds_write_b16_d16_hi v96, v81 offset:5360
	s_setprio 2
